# v14 plus cs/bw table prefetch by wave 4 at tile start, counted epilogue-start waits, ALIGN barrier after row-stat block
# speedup vs baseline: 1.0013x; 1.0013x over previous
; #define PG8_LAS __attribute__((address_space(3)))
;     __device__ __forceinline__ void load(const Unit& u, int wr, int wc, int fr, int fq, const f32x4 pfa, const f32x4 pfb) {
;     ...
;         if (tid >= 256 && tid < 320) { const int t4 = 4 * (tid - 256); const f32x4 cc = *(const f32x4*)(cs + u.pn * BM + t4), bb = *(const f32x4*)(bw + u.pn * BM + t4);
;             *(PG8_LAS f32x4*)(CB + t4) = cc; *(PG8_LAS f32x4*)(CB + 256 + t4) = bb; }
.LBB0_89:
	s_cmp_eq_u32 s67, 4
	s_cbranch_scc0 .Lnocs_7
	s_lshl_b32 s99, s13, 10
	v_readlane_b32 s100, v255, 16
	v_readlane_b32 s101, v255, 18
	v_lshlrev_b32_e32 v2, 4, v232
	v_mov_b32_e32 v3, 0
	v_lshlrev_b32_e32 v6, 4, v232
	v_mov_b32_e32 v7, 0
	s_add_u32 s100, s100, s99
	s_addc_u32 s101, s101, 0
	v_lshl_add_u64 v[2:3], s[100:101], 0, v[2:3]
	s_add_u32 s100, s44, s99
	s_addc_u32 s101, s45, 0
	v_lshl_add_u64 v[6:7], s[100:101], 0, v[6:7]
	global_load_dwordx4 v[2:5], v[2:3], off
	global_load_dwordx4 v[6:9], v[6:7], off

; #define PG8_LAS __attribute__((address_space(3)))
; #define PG8_BAR __builtin_amdgcn_s_barrier()
; template <class Epi, class Sched, bool ALIGN_EPI = false, bool SP2 = false>
; __device__ __forceinline__ void gemm_phase(PG8_LAS unsigned char* lds, const Gemm g, const Sched& S, const Epi& E, const int wave_id) {
;     ...
;         if constexpr (ALIGN_EPI) { if (wr == 0) PG8_BAR; }
;     __device__ __forceinline__ void load(const Unit& u, int wr, int wc, int fr, int fq, const f32x4 pfa, const f32x4 pfb) {
;         if (!st) return;
;         const int tid = (wr * 4 + wc) * 64 + fq * 16 + fr;
;         if (tid < 256) { const float mean = ((pfa[0] + pfa[2]) + (pfb[0] + pfb[2])) * (1.f / 1024.f), var = ((pfa[1] + pfa[3]) + (pfb[1] + pfb[3])) * (1.f / 1024.f) - mean * mean;
;             const f32x2_t mrv = {mean, 1.0f / sqrtf(var + LN_EPS)};
;             *(PG8_LAS f32x2_t*)(T + 2 * tid) = mrv;
;             if (mr_out && u.pn == 0) *(f32x2_t*)(mr_out + 2 * (unsigned)(u.pm * BM + tid)) = mrv; }
;         PG8_LAS float* CB = T + 1024;
;         if (tid >= 256 && tid < 320) { const int t4 = 4 * (tid - 256); const f32x4 cc = *(const f32x4*)(cs + u.pn * BM + t4), bb = *(const f32x4*)(bw + u.pn * BM + t4);
;             *(PG8_LAS f32x4*)(CB + t4) = cc; *(PG8_LAS f32x4*)(CB + 256 + t4) = bb; }
.LBB0_93:
	v_mov_b32_e32 v209, v202
	s_movk_i32 s4, 0x100
	v_add_u32_e32 v140, v205, v209
	v_cmp_gt_i32_e32 vcc, s4, v140
	s_and_saveexec_b64 s[28:29], vcc
	s_cbranch_execz .LBB0_96
	s_waitcnt vmcnt(8)
	v_pk_add_f32 v[138:139], v[6:7], v[8:9]
	v_pk_add_f32 v[142:143], v[2:3], v[4:5]
	s_mov_b32 s4, 0x3a800000
	v_pk_add_f32 v[138:139], v[138:139], v[142:143]
	s_cmp_lg_u32 s13, 0
	v_pk_mul_f32 v[138:139], v[138:139], s[4:5] op_sel_hi:[1,0]
	s_nop 0
	v_fma_f32 v0, -v138, v138, v139
	v_add_f32_e32 v0, 0x3727c5ac, v0
	v_mul_f32_e32 v139, 0x4f800000, v0
	v_cmp_gt_f32_e32 vcc, s41, v0
	s_nop 1
	v_cndmask_b32_e32 v0, v0, v139, vcc
	v_sqrt_f32_e32 v139, v0
	s_nop 0
	v_add_u32_e32 v141, -1, v139
	v_fma_f32 v142, -v141, v139, v0
	v_cmp_ge_f32_e64 s[8:9], 0, v142
	v_add_u32_e32 v142, 1, v139
	s_nop 0
	v_cndmask_b32_e64 v141, v139, v141, s[8:9]
	v_fma_f32 v139, -v142, v139, v0
	v_cmp_lt_f32_e64 s[8:9], 0, v139
	s_nop 1
	v_cndmask_b32_e64 v139, v141, v142, s[8:9]
	v_mul_f32_e32 v141, 0x37800000, v139
	v_cndmask_b32_e32 v139, v139, v141, vcc
	v_cmp_class_f32_e32 vcc, v0, v226
	s_nop 1
	v_cndmask_b32_e32 v0, v139, v0, vcc
	v_div_scale_f32 v139, s[4:5], v0, v0, 1.0
	v_rcp_f32_e32 v141, v139
	s_nop 0
	v_fma_f32 v142, -v139, v141, 1.0
	v_fmac_f32_e32 v141, v142, v141
	v_div_scale_f32 v142, vcc, 1.0, v0, 1.0
	v_mul_f32_e32 v143, v142, v141
	v_fma_f32 v144, -v139, v143, v142
	v_fmac_f32_e32 v143, v144, v141
	v_fma_f32 v139, -v139, v143, v142
	v_div_fmas_f32 v139, v139, v141, v143
	v_div_fixup_f32 v139, v139, v0, 1.0
	v_lshl_add_u32 v0, v140, 3, 0
	v_add_u32_e32 v0, 0x22000, v0
	ds_write_b64 v0, v[138:139]
	s_cbranch_scc1 .LBB0_96
	s_lshl_b32 s4, s26, 9
	v_lshl_add_u32 v0, v140, 1, s4
	v_readlane_b32 s4, v255, 22
	v_readlane_b32 s5, v255, 23
	s_nop 1
	v_lshl_add_u64 v[142:143], v[0:1], 2, s[4:5]
	global_store_dwordx2 v[142:143], v[138:139], off
.LBB0_96:
	s_or_b64 exec, exec, s[28:29]
	s_and_b64 vcc, exec, s[16:17]
	s_cbranch_vccz .Lab_10
	s_barrier
.Lab_10:
	v_and_b32_e32 v0, 0xffffffc0, v140
	s_movk_i32 s4, 0x100
	v_cmp_ne_u32_e32 vcc, s4, v0
	s_and_saveexec_b64 s[8:9], vcc
	s_xor_b64 s[8:9], exec, s[8:9]
	s_lshl_b32 s4, s13, 8
	s_or_saveexec_b64 s[8:9], s[8:9]
	v_mov_b32_e32 v0, s4
	s_xor_b64 exec, exec, s[8:9]
	s_cbranch_execz .LBB0_100
	s_lshl_b32 s4, s13, 8
	s_ashr_i32 s5, s4, 31
	s_lshl_b64 s[10:11], s[4:5], 2
	v_readlane_b32 s5, v255, 16
	s_add_u32 s28, s5, s10
	v_readlane_b32 s5, v255, 18
	v_lshl_add_u32 v0, v140, 2, v238
	s_addc_u32 s29, s5, s11
	v_lshlrev_b64 v[138:139], 2, v[0:1]
	s_add_u32 s10, s44, s10
	v_lshl_add_u64 v[142:143], s[28:29], 0, v[138:139]
	s_addc_u32 s11, s45, s11
	v_lshl_add_u64 v[138:139], s[10:11], 0, v[138:139]
	s_nop 0
	v_lshl_add_u32 v138, v140, 4, 0
	v_lshl_add_u32 v0, v0, 2, 0
	v_add_u32_e32 v138, 0x22000, v138
	v_add_u32_e32 v0, 0x23400, v0
	s_waitcnt vmcnt(8)
	ds_write_b128 v138, v[2:5]
	ds_write_b128 v0, v[6:9]
	v_mov_b32_e32 v0, s4

; #define PG8_LAS __attribute__((address_space(3)))
;     __device__ __forceinline__ void load(const Unit& u, int wr, int wc, int fr, int fq, const f32x4 pfa, const f32x4 pfb) {
;     ...
;         if (tid >= 256 && tid < 320) { const int t4 = 4 * (tid - 256); const f32x4 cc = *(const f32x4*)(cs + u.pn * BM + t4), bb = *(const f32x4*)(bw + u.pn * BM + t4);
;             *(PG8_LAS f32x4*)(CB + t4) = cc; *(PG8_LAS f32x4*)(CB + 256 + t4) = bb; }
.LBB0_575:
	s_cmp_eq_u32 s67, 4
	s_cbranch_scc0 .Lnocs_8
	s_lshl_b32 s99, s24, 10
	v_readlane_b32 s100, v255, 16
	v_readlane_b32 s101, v255, 18
	v_lshlrev_b32_e32 v2, 4, v232
	v_mov_b32_e32 v3, 0
	v_lshlrev_b32_e32 v6, 4, v232
	v_mov_b32_e32 v7, 0
	s_add_u32 s100, s100, s99
	s_addc_u32 s101, s101, 0
	v_lshl_add_u64 v[2:3], s[100:101], 0, v[2:3]
	s_add_u32 s100, s37, s99
	s_addc_u32 s101, s38, 0
	v_lshl_add_u64 v[6:7], s[100:101], 0, v[6:7]
	global_load_dwordx4 v[2:5], v[2:3], off
	global_load_dwordx4 v[6:9], v[6:7], off

; #define PG8_LAS __attribute__((address_space(3)))
; #define PG8_BAR __builtin_amdgcn_s_barrier()
; template <class Epi, class Sched, bool ALIGN_EPI = false, bool SP2 = false>
; __device__ __forceinline__ void gemm_phase(PG8_LAS unsigned char* lds, const Gemm g, const Sched& S, const Epi& E, const int wave_id) {
;     ...
;         if constexpr (ALIGN_EPI) { if (wr == 0) PG8_BAR; }
;     __device__ __forceinline__ void load(const Unit& u, int wr, int wc, int fr, int fq, const f32x4 pfa, const f32x4 pfb) {
;         if (!st) return;
;         const int tid = (wr * 4 + wc) * 64 + fq * 16 + fr;
;         if (tid < 256) { const float mean = ((pfa[0] + pfa[2]) + (pfb[0] + pfb[2])) * (1.f / 1024.f), var = ((pfa[1] + pfa[3]) + (pfb[1] + pfb[3])) * (1.f / 1024.f) - mean * mean;
;             const f32x2_t mrv = {mean, 1.0f / sqrtf(var + LN_EPS)};
;             *(PG8_LAS f32x2_t*)(T + 2 * tid) = mrv;
;             if (mr_out && u.pn == 0) *(f32x2_t*)(mr_out + 2 * (unsigned)(u.pm * BM + tid)) = mrv; }
;         PG8_LAS float* CB = T + 1024;
;         if (tid >= 256 && tid < 320) { const int t4 = 4 * (tid - 256); const f32x4 cc = *(const f32x4*)(cs + u.pn * BM + t4), bb = *(const f32x4*)(bw + u.pn * BM + t4);
;             *(PG8_LAS f32x4*)(CB + t4) = cc; *(PG8_LAS f32x4*)(CB + 256 + t4) = bb; }
.LBB0_579:
	v_mov_b32_e32 v204, v208
	s_movk_i32 s0, 0x100
	v_add_u32_e32 v140, v212, v204
	v_cmp_gt_i32_e32 vcc, s0, v140
	s_and_saveexec_b64 s[26:27], vcc
	s_cbranch_execz .LBB0_582
	s_waitcnt vmcnt(8)
	v_pk_add_f32 v[138:139], v[6:7], v[8:9]
	v_pk_add_f32 v[142:143], v[2:3], v[4:5]
	s_mov_b32 s0, 0x3a800000
	v_pk_add_f32 v[138:139], v[138:139], v[142:143]
	s_cmp_lg_u32 s24, 0
	v_pk_mul_f32 v[138:139], v[138:139], s[0:1] op_sel_hi:[1,0]
	s_nop 0
	v_fma_f32 v0, -v138, v138, v139
	v_add_f32_e32 v0, 0x3727c5ac, v0
	v_mul_f32_e32 v139, 0x4f800000, v0
	v_cmp_gt_f32_e32 vcc, s41, v0
	s_nop 1
	v_cndmask_b32_e32 v0, v0, v139, vcc
	v_sqrt_f32_e32 v139, v0
	s_nop 0
	v_add_u32_e32 v141, -1, v139
	v_fma_f32 v142, -v141, v139, v0
	v_cmp_ge_f32_e64 s[8:9], 0, v142
	v_add_u32_e32 v142, 1, v139
	s_nop 0
	v_cndmask_b32_e64 v141, v139, v141, s[8:9]
	v_fma_f32 v139, -v142, v139, v0
	v_cmp_lt_f32_e64 s[8:9], 0, v139
	s_nop 1
	v_cndmask_b32_e64 v139, v141, v142, s[8:9]
	v_mul_f32_e32 v141, 0x37800000, v139
	v_cndmask_b32_e32 v139, v139, v141, vcc
	v_cmp_class_f32_e32 vcc, v0, v226
	s_nop 1
	v_cndmask_b32_e32 v0, v139, v0, vcc
	v_div_scale_f32 v139, s[0:1], v0, v0, 1.0
	v_rcp_f32_e32 v141, v139
	s_nop 0
	v_fma_f32 v142, -v139, v141, 1.0
	v_fmac_f32_e32 v141, v142, v141
	v_div_scale_f32 v142, vcc, 1.0, v0, 1.0
	v_mul_f32_e32 v143, v142, v141
	v_fma_f32 v144, -v139, v143, v142
	v_fmac_f32_e32 v143, v144, v141
	v_fma_f32 v139, -v139, v143, v142
	v_div_fmas_f32 v139, v139, v141, v143
	v_div_fixup_f32 v139, v139, v0, 1.0
	v_lshl_add_u32 v0, v140, 3, 0
	v_add_u32_e32 v0, 0x22000, v0
	ds_write_b64 v0, v[138:139]
	s_cbranch_scc1 .LBB0_582
	s_lshl_b32 s0, s22, 9
	v_lshl_add_u32 v0, v140, 1, s0
	v_readlane_b32 s0, v255, 20
	v_readlane_b32 s1, v255, 21
	s_nop 1
	v_lshl_add_u64 v[142:143], v[0:1], 2, s[0:1]
	global_store_dwordx2 v[142:143], v[138:139], off
.LBB0_582:
	s_or_b64 exec, exec, s[26:27]
	s_and_b64 vcc, exec, s[10:11]
	s_cbranch_vccz .Lab_11
	s_barrier
.Lab_11:
	v_and_b32_e32 v0, 0xffffffc0, v140
	s_movk_i32 s0, 0x100
	v_cmp_eq_u32_e32 vcc, s0, v0
	s_and_saveexec_b64 s[8:9], vcc
	s_cbranch_execz .LBB0_584
	s_lshl_b32 s0, s24, 8
	s_ashr_i32 s1, s0, 31
	s_lshl_b64 s[0:1], s[0:1], 2
	v_readlane_b32 s3, v255, 16
	s_add_u32 s4, s3, s0
	v_readlane_b32 s3, v255, 18
	s_addc_u32 s5, s3, s1
	v_lshl_add_u32 v0, v140, 2, v238
	s_add_u32 s0, s37, s0
	v_lshlrev_b64 v[138:139], 2, v[0:1]
	s_addc_u32 s1, s38, s1
	v_lshl_add_u64 v[142:143], s[4:5], 0, v[138:139]
	v_lshl_add_u64 v[138:139], s[0:1], 0, v[138:139]
	v_lshl_add_u32 v0, v0, 2, 0
	v_lshl_add_u32 v138, v140, 4, 0
	v_add_u32_e32 v138, 0x22000, v138
	v_add_u32_e32 v0, 0x23400, v0
	s_waitcnt vmcnt(8)
	ds_write_b128 v138, v[2:5]
	ds_write_b128 v0, v[6:9]

; #define PG8_LAS __attribute__((address_space(3)))
;     __device__ __forceinline__ void load(const Unit& u, int wr, int wc, int fr, int fq, const f32x4 pfa, const f32x4 pfb) {
;     ...
;         if (tid >= 256 && tid < 320) { const int t4 = 4 * (tid - 256); const f32x4 cc = *(const f32x4*)(cs + u.pn * BM + t4), bb = *(const f32x4*)(bw + u.pn * BM + t4);
;             *(PG8_LAS f32x4*)(CB + t4) = cc; *(PG8_LAS f32x4*)(CB + 256 + t4) = bb; }
.LBB0_626:
	s_cmp_eq_u32 s67, 4
	s_cbranch_scc0 .Lnocs_9
	s_lshl_b32 s99, s24, 10
	v_readlane_b32 s100, v255, 16
	v_readlane_b32 s101, v255, 18
	v_lshlrev_b32_e32 v2, 4, v232
	v_mov_b32_e32 v3, 0
	v_lshlrev_b32_e32 v6, 4, v232
	v_mov_b32_e32 v7, 0
	s_add_u32 s100, s100, s99
	s_addc_u32 s101, s101, 0
	v_lshl_add_u64 v[2:3], s[100:101], 0, v[2:3]
	v_readlane_b32 s100, v255, 20
	v_readlane_b32 s101, v255, 22
	s_nop 0
	s_add_u32 s100, s100, s99
	s_addc_u32 s101, s101, 0
	v_lshl_add_u64 v[6:7], s[100:101], 0, v[6:7]
	global_load_dwordx4 v[2:5], v[2:3], off
	global_load_dwordx4 v[6:9], v[6:7], off

; #define PG8_LAS __attribute__((address_space(3)))
;     __device__ __forceinline__ void load(const Unit& u, int wr, int wc, int fr, int fq, const f32x4 pfa, const f32x4 pfb) {
;         if (!st) return;
;         const int tid = (wr * 4 + wc) * 64 + fq * 16 + fr;
;         if (tid < 256) { const float mean = ((pfa[0] + pfa[2]) + (pfb[0] + pfb[2])) * (1.f / 1024.f), var = ((pfa[1] + pfa[3]) + (pfb[1] + pfb[3])) * (1.f / 1024.f) - mean * mean;
;             const f32x2_t mrv = {mean, 1.0f / sqrtf(var + LN_EPS)};
;             *(PG8_LAS f32x2_t*)(T + 2 * tid) = mrv;
;             if (mr_out && u.pn == 0) *(f32x2_t*)(mr_out + 2 * (unsigned)(u.pm * BM + tid)) = mrv; }
;         PG8_LAS float* CB = T + 1024;
;         if (tid >= 256 && tid < 320) { const int t4 = 4 * (tid - 256); const f32x4 cc = *(const f32x4*)(cs + u.pn * BM + t4), bb = *(const f32x4*)(bw + u.pn * BM + t4);
;             *(PG8_LAS f32x4*)(CB + t4) = cc; *(PG8_LAS f32x4*)(CB + 256 + t4) = bb; }
.LBB0_630:
	v_mov_b32_e32 v193, v201
	s_andn2_b64 vcc, exec, s[4:5]
	s_cbranch_vccnz .LBB0_637
	v_add_u32_e32 v116, v242, v193
	s_movk_i32 s0, 0x100
	v_cmp_gt_i32_e32 vcc, s0, v116
	s_and_saveexec_b64 s[26:27], vcc
	s_cbranch_execz .LBB0_634
	s_waitcnt vmcnt(8)
	v_pk_add_f32 v[114:115], v[6:7], v[8:9]
	v_pk_add_f32 v[118:119], v[2:3], v[4:5]
	s_mov_b32 s0, 0x3a800000
	v_pk_add_f32 v[114:115], v[114:115], v[118:119]
	s_cmp_lg_u32 s24, 0
	v_pk_mul_f32 v[114:115], v[114:115], s[0:1] op_sel_hi:[1,0]
	s_nop 0
	v_fma_f32 v0, -v114, v114, v115
	v_add_f32_e32 v0, 0x3727c5ac, v0
	v_mul_f32_e32 v115, 0x4f800000, v0
	v_cmp_gt_f32_e32 vcc, s41, v0
	s_nop 1
	v_cndmask_b32_e32 v0, v0, v115, vcc
	v_sqrt_f32_e32 v115, v0
	s_nop 0
	v_add_u32_e32 v117, -1, v115
	v_fma_f32 v118, -v117, v115, v0
	v_cmp_ge_f32_e64 s[8:9], 0, v118
	v_add_u32_e32 v118, 1, v115
	s_nop 0
	v_cndmask_b32_e64 v117, v115, v117, s[8:9]
	v_fma_f32 v115, -v118, v115, v0
	v_cmp_lt_f32_e64 s[8:9], 0, v115
	s_nop 1
	v_cndmask_b32_e64 v115, v117, v118, s[8:9]
	v_mul_f32_e32 v117, 0x37800000, v115
	v_cndmask_b32_e32 v115, v115, v117, vcc
	v_cmp_class_f32_e32 vcc, v0, v226
	s_nop 1
	v_cndmask_b32_e32 v0, v115, v0, vcc
	v_div_scale_f32 v115, s[8:9], v0, v0, 1.0
	v_rcp_f32_e32 v117, v115
	s_nop 0
	v_fma_f32 v118, -v115, v117, 1.0
	v_fmac_f32_e32 v117, v118, v117
	v_div_scale_f32 v118, vcc, 1.0, v0, 1.0
	v_mul_f32_e32 v119, v118, v117
	v_fma_f32 v120, -v115, v119, v118
	v_fmac_f32_e32 v119, v120, v117
	v_fma_f32 v115, -v115, v119, v118
	v_div_fmas_f32 v115, v115, v117, v119
	v_div_fixup_f32 v115, v115, v0, 1.0
	v_lshl_add_u32 v0, v116, 3, 0
	v_add_u32_e32 v0, 0x22000, v0
	ds_write_b64 v0, v[114:115]
	s_cbranch_scc1 .LBB0_634
	s_lshl_b32 s0, s22, 9
	v_lshl_add_u32 v0, v116, 1, s0
	v_readlane_b32 s0, v255, 28
	v_readlane_b32 s1, v255, 29
	s_nop 1
	v_lshl_add_u64 v[118:119], v[0:1], 2, s[0:1]
	global_store_dwordx2 v[118:119], v[114:115], off
.LBB0_634:
	s_or_b64 exec, exec, s[26:27]
	v_and_b32_e32 v0, 0xffffffc0, v116
	s_movk_i32 s0, 0x100
	v_cmp_eq_u32_e32 vcc, s0, v0
	s_and_saveexec_b64 s[8:9], vcc
	s_cbranch_execz .LBB0_636
	s_lshl_b32 s26, s24, 8
	s_ashr_i32 s27, s26, 31
	s_lshl_b64 s[26:27], s[26:27], 2
	v_readlane_b32 s0, v255, 16
	s_add_u32 s28, s0, s26
	v_readlane_b32 s0, v255, 18
	s_addc_u32 s29, s0, s27
	v_readlane_b32 s0, v255, 20
	v_lshl_add_u32 v0, v116, 2, v238
	s_add_u32 s26, s0, s26
	v_readlane_b32 s0, v255, 22
	v_lshlrev_b64 v[114:115], 2, v[0:1]
	s_addc_u32 s27, s0, s27
	v_lshl_add_u64 v[118:119], s[28:29], 0, v[114:115]
	v_lshl_add_u64 v[114:115], s[26:27], 0, v[114:115]
	v_lshl_add_u32 v0, v0, 2, 0
	v_lshl_add_u32 v114, v116, 4, 0
	v_add_u32_e32 v114, 0x22000, v114
	v_add_u32_e32 v0, 0x23400, v0
	s_waitcnt vmcnt(8)
	ds_write_b128 v114, v[2:5]
	ds_write_b128 v0, v[6:9]
